# GLA intra-chunk Am tiles: all fragment reads issued before the MFMAs; deeper Qd read-ahead
# speedup vs baseline: 1.0281x; 1.0025x over previous
; __device__ __forceinline__ unsigned opq(unsigned x) { asm volatile("" : "+v"(x)); return x; }
; template <int VAR> __device__ __forceinline__ void gla_chunk_item(const Frame& F, int item, bool last) {
;     ...
;         for (int tt = 0; tt < 2; ++tt) {
;             const int t = 2 * w + tt, jt = t >> 2, it = t & 3;
;             f32x4 acc = (f32x4){0.f, 0.f, 0.f, 0.f};
;             if (jt <= it) {
;                 const unsigned ak = a_f8 + G_KI + jt * (16 * GQ_LD * 2), aq = a_f8 + G_QD + it * (16 * GQ_LD * 2);
; #pragma unroll
;                 for (int s = 0; s < 8; ++s) {
;                     const bf16x8 a = LD_(bf16x8, ak + 64 * s);
;                     const bf16x8 bb = LD_(bf16x8, aq + 64 * s);
;                     acc = __builtin_amdgcn_mfma_f32_16x16x32_bf16(a, bb, acc, 0, 0, 0);
;                 }
;             }
;             const int i = 16 * it + l16, j0 = 16 * jt + 4 * g;
;             const float m0 = (j0 + 0 <= i) ? acc[0] : 0.f, m1 = (j0 + 1 <= i) ? acc[1] : 0.f, m2 = (j0 + 2 <= i) ? acc[2] : 0.f, m3 = (j0 + 3 <= i) ? acc[3] : 0.f;
;             ST_(v2u, G_AM + (i * GT_LD + j0) * 2) = (v2u){pg8::cvt_pk_bf16(m0, m1), pg8::cvt_pk_bf16(m2, m3)};
;         }
;         __syncthreads();
;         if (VAR != 3)
;         {
;             const unsigned a_f4 = opq(G_QD + (l16 * GQ_LD + 4 * g) * 2), a_t8 = opq((l16 * GT_LD + 8 * g) * 2), a_ebl = opq(G_EBL + 16 * g);
;             const unsigned a_vtr = opq(G_VT + ((8 * g + (l16 >> 2)) * GV_LD + 16 * w + 4 * (l16 & 3)) * 2);
;             const unsigned a_os = opq(G_KI + ((4 * g) * GV_LD + 16 * w + l16) * 2);
;             f32x4 O[4];
; #pragma unroll
;             for (int mt = 0; mt < 4; ++mt) O[mt] = (f32x4){0.f, 0.f, 0.f, 0.f};
; #pragma unroll
;             for (int s = 0; s < 8; ++s) {
;                 const bf16x8 bs = pack8(S[2 * s], S[2 * s + 1]);
; #pragma unroll
;                 for (int mt = 0; mt < 4; ++mt) {
;                     const v2u a0 = LD_(v2u, a_f4 + (16 * mt * GQ_LD + 32 * s) * 2);
;                     const v2u a1 = LD_(v2u, a_f4 + (16 * mt * GQ_LD + 32 * s + 16) * 2);
;                     const bf16x8 a = __builtin_bit_cast(bf16x8, (v4u){a0.x, a0.y, a1.x, a1.y});
;                     O[mt] = __builtin_amdgcn_mfma_f32_16x16x32_bf16(a, bs, O[mt], 0, 0, 0);
;                 }
;                 asm volatile("" ::: "memory");
;             }
.LBB0_814:
	v_mov_b32_e32 v76, v166
	s_mul_i32 s45, s97, 0x2100
	v_add_u32_e32 v77, 0, v76
	v_mov_b32_e32 v76, 0
	s_and_b64 vcc, exec, s[2:3]
	v_add_u32_e32 v82, s53, v77
	v_add_u32_e32 v83, s45, v77
	v_mov_b32_e32 v78, 0
	v_mov_b32_e32 v79, 0
	v_mov_b32_e32 v80, 0
	v_mov_b32_e32 v81, 0
	s_cbranch_vccnz .LBB0_816
	ds_read_b128 v[92:95], v83 offset:33792
	ds_read_b128 v[96:99], v82
	ds_read_b128 v[100:103], v83 offset:33856
	ds_read_b128 v[104:107], v82 offset:64
	ds_read_b128 v[108:111], v83 offset:33920
	ds_read_b128 v[112:115], v82 offset:128
	ds_read_b128 v[116:119], v83 offset:33984
	ds_read_b128 v[120:123], v82 offset:192
	ds_read_b128 v[124:127], v83 offset:34048
	ds_read_b128 v[128:131], v82 offset:256
	ds_read_b128 v[132:135], v83 offset:34112
	ds_read_b128 v[136:139], v82 offset:320
	ds_read_b128 v[140:143], v83 offset:34176
	ds_read_b128 v[144:147], v82 offset:384
	ds_read_b128 v[198:201], v83 offset:34240
	ds_read_b128 v[228:231], v82 offset:448
	s_waitcnt lgkmcnt(14)
	v_mfma_f32_16x16x32_bf16 v[78:81], v[92:95], v[96:99], 0
	s_waitcnt lgkmcnt(12)
	v_mfma_f32_16x16x32_bf16 v[78:81], v[100:103], v[104:107], v[78:81]
	s_waitcnt lgkmcnt(10)
	v_mfma_f32_16x16x32_bf16 v[78:81], v[108:111], v[112:115], v[78:81]
	s_waitcnt lgkmcnt(8)
	v_mfma_f32_16x16x32_bf16 v[78:81], v[116:119], v[120:123], v[78:81]
	s_waitcnt lgkmcnt(6)
	v_mfma_f32_16x16x32_bf16 v[78:81], v[124:127], v[128:131], v[78:81]
	s_waitcnt lgkmcnt(4)
	v_mfma_f32_16x16x32_bf16 v[78:81], v[132:135], v[136:139], v[78:81]
	s_waitcnt lgkmcnt(2)
	v_mfma_f32_16x16x32_bf16 v[78:81], v[140:143], v[144:147], v[78:81]
	s_waitcnt lgkmcnt(0)
	v_mfma_f32_16x16x32_bf16 v[78:81], v[198:201], v[228:231], v[78:81]
.LBB0_816:
	s_nop 7
	v_cndmask_b32_e64 v77, v78, 0, s[16:17]
	v_cndmask_b32_e64 v78, 0, v79, s[18:19]
	v_cndmask_b32_e64 v79, v80, 0, s[20:21]
	v_cndmask_b32_e64 v80, v81, 0, s[22:23]
	v_cvt_pk_bf16_f32 v78, v77, v78
	v_cvt_pk_bf16_f32 v79, v79, v80
	ds_write_b64 v174, v[78:79]
	s_and_b64 vcc, exec, s[4:5]
	v_mov_b32_e32 v77, 0
	v_mov_b32_e32 v78, 0
	v_mov_b32_e32 v79, 0
	s_cbranch_vccnz .LBB0_818
	ds_read_b128 v[92:95], v83 offset:33792
	ds_read_b128 v[96:99], v82 offset:8448
	ds_read_b128 v[100:103], v83 offset:33856
	ds_read_b128 v[104:107], v82 offset:8512
	ds_read_b128 v[108:111], v83 offset:33920
	ds_read_b128 v[112:115], v82 offset:8576
	ds_read_b128 v[116:119], v83 offset:33984
	ds_read_b128 v[120:123], v82 offset:8640
	ds_read_b128 v[124:127], v83 offset:34048
	ds_read_b128 v[128:131], v82 offset:8704
	ds_read_b128 v[132:135], v83 offset:34112
	ds_read_b128 v[136:139], v82 offset:8768
	ds_read_b128 v[140:143], v83 offset:34176
	ds_read_b128 v[144:147], v82 offset:8832
	ds_read_b128 v[198:201], v83 offset:34240
	ds_read_b128 v[228:231], v82 offset:8896
	s_waitcnt lgkmcnt(14)
	v_mfma_f32_16x16x32_bf16 v[76:79], v[92:95], v[96:99], 0
	s_waitcnt lgkmcnt(12)
	v_mfma_f32_16x16x32_bf16 v[76:79], v[100:103], v[104:107], v[76:79]
	s_waitcnt lgkmcnt(10)
	v_mfma_f32_16x16x32_bf16 v[76:79], v[108:111], v[112:115], v[76:79]
	s_waitcnt lgkmcnt(8)
	v_mfma_f32_16x16x32_bf16 v[76:79], v[116:119], v[120:123], v[76:79]
	s_waitcnt lgkmcnt(6)
	v_mfma_f32_16x16x32_bf16 v[76:79], v[124:127], v[128:131], v[76:79]
	s_waitcnt lgkmcnt(4)
	v_mfma_f32_16x16x32_bf16 v[76:79], v[132:135], v[136:139], v[76:79]
	s_waitcnt lgkmcnt(2)
	v_mfma_f32_16x16x32_bf16 v[76:79], v[140:143], v[144:147], v[76:79]
	s_waitcnt lgkmcnt(0)
	v_mfma_f32_16x16x32_bf16 v[76:79], v[198:201], v[228:231], v[76:79]
.LBB0_818:
	s_nop 7
	v_cndmask_b32_e64 v76, v76, 0, s[24:25]
	v_cndmask_b32_e64 v77, 0, v77, s[26:27]
	v_cndmask_b32_e64 v78, v78, 0, s[28:29]
	v_cndmask_b32_e64 v79, v79, 0, s[30:31]
	v_cvt_pk_bf16_f32 v76, v76, v77
	v_cvt_pk_bf16_f32 v77, v78, v79
	ds_write_b64 v175, v[76:77]
	v_mov_b32_e32 v77, v166
	s_waitcnt lgkmcnt(0)
	s_barrier
	v_mov_b32_e32 v84, v169
	v_mov_b32_e32 v100, v170
	v_mov_b32_e32 v76, v171
	v_mov_b32_e32 v101, v172
	v_add_u32_e32 v77, 0, v77
	ds_read_b128 v[78:81], v77
	v_cvt_pk_bf16_f32 v86, v72, v73
	v_cvt_pk_bf16_f32 v87, v74, v75
	v_cvt_pk_bf16_f32 v88, v68, v69
	v_cvt_pk_bf16_f32 v89, v70, v71
	v_add_u32_e32 v149, 0, v84
	v_add_u32_e32 v84, 0x1e000, v149
	s_waitcnt lgkmcnt(0)
	v_mfma_f32_16x16x32_bf16 v[90:93], v[78:81], v[86:89], 0
	v_add_u32_e32 v78, 0x2000, v77
	ds_read_b128 v[80:83], v78 offset:256
	v_add_u32_e32 v79, 0x4000, v77
	s_waitcnt lgkmcnt(0)
	v_mfma_f32_16x16x32_bf16 v[94:97], v[80:83], v[86:89], 0
	ds_read_b128 v[80:83], v79 offset:512
	s_and_b64 s[48:49], s[84:85], s[46:47]
	s_xor_b64 s[46:47], s[48:49], -1
	s_waitcnt lgkmcnt(0)
	v_mfma_f32_16x16x32_bf16 v[102:105], v[80:83], v[86:89], 0
	v_add_u32_e32 v80, 0x6000, v77
	ds_read_b128 v[106:109], v80 offset:768
	ds_read_b128 v[110:113], v77 offset:64
	ds_read_b128 v[116:119], v78 offset:320
	ds_read_b128 v[120:123], v79 offset:576
	ds_read_b128 v[124:127], v80 offset:832
	ds_read_b128 v[128:131], v77 offset:128
	ds_read_b128 v[132:135], v78 offset:384
	ds_read_b128 v[136:139], v79 offset:640
	ds_read_b128 v[140:143], v80 offset:896
	ds_read_b128 v[144:147], v77 offset:192
	ds_read_b128 v[198:201], v78 offset:448
	ds_read_b128 v[228:231], v79 offset:704
	s_waitcnt lgkmcnt(11)
	v_mfma_f32_16x16x32_bf16 v[86:89], v[106:109], v[86:89], 0
	v_cvt_pk_bf16_f32 v106, v64, v65
	v_cvt_pk_bf16_f32 v107, v66, v67
	v_cvt_pk_bf16_f32 v108, v60, v61
	v_cvt_pk_bf16_f32 v109, v62, v63
	s_and_b64 vcc, exec, s[48:49]
	s_waitcnt lgkmcnt(10)
	s_nop 0
	v_mfma_f32_16x16x32_bf16 v[90:93], v[110:113], v[106:109], v[90:93]
	ds_read_b128 v[110:113], v80 offset:960
	s_waitcnt lgkmcnt(10)
	v_mfma_f32_16x16x32_bf16 v[94:97], v[116:119], v[106:109], v[94:97]
	ds_read_b128 v[116:119], v77 offset:256
	s_waitcnt lgkmcnt(10)
; __device__ __forceinline__ unsigned f2bf(float f) { return pk2(f, 0.f) & 0xffffu; }
; template <int VAR> __device__ __forceinline__ void gla_chunk_item(const Frame& F, int item, bool last) {
;     ...
;             for (int s = 0; s < 8; ++s) {
;                 const bf16x8 bs = pack8(S[2 * s], S[2 * s + 1]);
; #pragma unroll
;                 for (int mt = 0; mt < 4; ++mt) {
;                     const v2u a0 = LD_(v2u, a_f4 + (16 * mt * GQ_LD + 32 * s) * 2);
;                     const v2u a1 = LD_(v2u, a_f4 + (16 * mt * GQ_LD + 32 * s + 16) * 2);
;                     const bf16x8 a = __builtin_bit_cast(bf16x8, (v4u){a0.x, a0.y, a1.x, a1.y});
;                     O[mt] = __builtin_amdgcn_mfma_f32_16x16x32_bf16(a, bs, O[mt], 0, 0, 0);
;                 }
;                 asm volatile("" ::: "memory");
;             }
;             const bf16x8 vb0 = tr8(L, a_vtr, a_vtr + 4 * GV_LD * 2);
;             const bf16x8 vb1 = tr8(L, a_vtr + 32 * GV_LD * 2, a_vtr + 36 * GV_LD * 2);
; #pragma unroll
;             for (int mt = 0; mt < 4; ++mt) {
;                 const bf16x8 a0 = LD_(bf16x8, a_t8 + G_AM + mt * (16 * GT_LD * 2));
;                 O[mt] = __builtin_amdgcn_mfma_f32_16x16x32_bf16(a0, vb0, O[mt], 0, 0, 0);
;                 if (mt >= 2) { const bf16x8 a1 = LD_(bf16x8, a_t8 + G_AM + mt * (16 * GT_LD * 2) + 64);
;                     O[mt] = __builtin_amdgcn_mfma_f32_16x16x32_bf16(a1, vb1, O[mt], 0, 0, 0); }
;             }
;             if (VAR == 0 && !(last && chunk < 4)) {
;                 const unsigned aos = a_os;
; #pragma unroll
;                 for (int mt = 0; mt < 4; ++mt)
; #pragma unroll
;                     for (int r = 0; r < 4; ++r) ST_(unsigned short, aos + (16 * mt + r) * (GV_LD * 2)) = (unsigned short)f2bf(O[mt][r]);
;             }
	v_mfma_f32_16x16x32_bf16 v[102:105], v[120:123], v[106:109], v[102:105]
	ds_read_b128 v[120:123], v78 offset:512
	s_waitcnt lgkmcnt(10)
	v_mfma_f32_16x16x32_bf16 v[86:89], v[124:127], v[106:109], v[86:89]
	ds_read_b128 v[124:127], v79 offset:768
	v_cvt_pk_bf16_f32 v106, v56, v57
	v_cvt_pk_bf16_f32 v107, v58, v59
	v_cvt_pk_bf16_f32 v108, v52, v53
	v_cvt_pk_bf16_f32 v109, v54, v55
	s_waitcnt lgkmcnt(10)
	s_nop 0
	v_mfma_f32_16x16x32_bf16 v[90:93], v[128:131], v[106:109], v[90:93]
	ds_read_b128 v[128:131], v80 offset:1024
	s_waitcnt lgkmcnt(10)
	v_mfma_f32_16x16x32_bf16 v[94:97], v[132:135], v[106:109], v[94:97]
	ds_read_b128 v[132:135], v77 offset:320
	s_waitcnt lgkmcnt(10)
	v_mfma_f32_16x16x32_bf16 v[102:105], v[136:139], v[106:109], v[102:105]
	ds_read_b128 v[136:139], v78 offset:576
	s_waitcnt lgkmcnt(10)
	v_mfma_f32_16x16x32_bf16 v[86:89], v[140:143], v[106:109], v[86:89]
	ds_read_b128 v[140:143], v79 offset:832
	v_cvt_pk_bf16_f32 v106, v48, v49
	v_cvt_pk_bf16_f32 v107, v50, v51
	v_cvt_pk_bf16_f32 v108, v44, v45
	v_cvt_pk_bf16_f32 v109, v46, v47
	s_waitcnt lgkmcnt(10)
	s_nop 0
	v_mfma_f32_16x16x32_bf16 v[90:93], v[144:147], v[106:109], v[90:93]
	ds_read_b128 v[144:147], v80 offset:1088
	s_waitcnt lgkmcnt(10)
	v_mfma_f32_16x16x32_bf16 v[94:97], v[198:201], v[106:109], v[94:97]
	ds_read_b128 v[198:201], v77 offset:384
	s_waitcnt lgkmcnt(10)
	v_mfma_f32_16x16x32_bf16 v[102:105], v[228:231], v[106:109], v[102:105]
	ds_read_b128 v[228:231], v78 offset:640
	s_waitcnt lgkmcnt(10)
	v_mfma_f32_16x16x32_bf16 v[86:89], v[110:113], v[106:109], v[86:89]
	ds_read_b128 v[110:113], v79 offset:896
	v_cvt_pk_bf16_f32 v106, v40, v41
	v_cvt_pk_bf16_f32 v107, v42, v43
	v_cvt_pk_bf16_f32 v108, v36, v37
	v_cvt_pk_bf16_f32 v109, v38, v39
	s_waitcnt lgkmcnt(10)
	s_nop 0
	v_mfma_f32_16x16x32_bf16 v[90:93], v[116:119], v[106:109], v[90:93]
	ds_read_b128 v[116:119], v80 offset:1152
	s_waitcnt lgkmcnt(10)
	v_mfma_f32_16x16x32_bf16 v[94:97], v[120:123], v[106:109], v[94:97]
	ds_read_b128 v[120:123], v77 offset:448
	s_waitcnt lgkmcnt(10)
	v_mfma_f32_16x16x32_bf16 v[102:105], v[124:127], v[106:109], v[102:105]
	ds_read_b128 v[124:127], v78 offset:704
	s_waitcnt lgkmcnt(10)
	v_mfma_f32_16x16x32_bf16 v[86:89], v[128:131], v[106:109], v[86:89]
	v_cvt_pk_bf16_f32 v106, v32, v33
	v_cvt_pk_bf16_f32 v107, v34, v35
	v_cvt_pk_bf16_f32 v108, v28, v29
	v_cvt_pk_bf16_f32 v109, v30, v31
	s_waitcnt lgkmcnt(9)
	s_nop 0
	v_mfma_f32_16x16x32_bf16 v[90:93], v[132:135], v[106:109], v[90:93]
	s_waitcnt lgkmcnt(8)
	v_mfma_f32_16x16x32_bf16 v[94:97], v[136:139], v[106:109], v[94:97]
	s_waitcnt lgkmcnt(7)
	v_mfma_f32_16x16x32_bf16 v[102:105], v[140:143], v[106:109], v[102:105]
	s_waitcnt lgkmcnt(6)
	v_mfma_f32_16x16x32_bf16 v[86:89], v[144:147], v[106:109], v[86:89]
	v_cvt_pk_bf16_f32 v106, v24, v25
	v_cvt_pk_bf16_f32 v107, v26, v27
	v_cvt_pk_bf16_f32 v108, v20, v21
	v_cvt_pk_bf16_f32 v109, v22, v23
	s_waitcnt lgkmcnt(5)
	s_nop 0
	v_mfma_f32_16x16x32_bf16 v[90:93], v[198:201], v[106:109], v[90:93]
	s_waitcnt lgkmcnt(4)
	v_mfma_f32_16x16x32_bf16 v[94:97], v[228:231], v[106:109], v[94:97]
	s_waitcnt lgkmcnt(3)
	v_mfma_f32_16x16x32_bf16 v[102:105], v[110:113], v[106:109], v[102:105]
	s_waitcnt lgkmcnt(2)
	v_mfma_f32_16x16x32_bf16 v[86:89], v[116:119], v[106:109], v[86:89]
	v_cvt_pk_bf16_f32 v106, v16, v17
	v_cvt_pk_bf16_f32 v107, v18, v19
	v_cvt_pk_bf16_f32 v108, v4, v5
	v_cvt_pk_bf16_f32 v109, v6, v7
	s_waitcnt lgkmcnt(1)
	s_nop 0
	v_mfma_f32_16x16x32_bf16 v[90:93], v[120:123], v[106:109], v[90:93]
	s_waitcnt lgkmcnt(0)
	v_mfma_f32_16x16x32_bf16 v[94:97], v[124:127], v[106:109], v[94:97]
	ds_read_b128 v[110:113], v79 offset:960
	ds_read_b128 v[78:81], v80 offset:1216
	s_waitcnt lgkmcnt(1)
	v_mfma_f32_16x16x32_bf16 v[102:105], v[110:113], v[106:109], v[102:105]
	s_waitcnt lgkmcnt(0)
	v_mfma_f32_16x16x32_bf16 v[106:109], v[78:81], v[106:109], v[86:89]
	v_add_u32_e32 v78, 0, v76
	ds_read_b64_tr_b16 v[80:81], v78
	ds_read_b64_tr_b16 v[82:83], v78 offset:1088
	ds_read_b64_tr_b16 v[76:77], v78 offset:8704
	ds_read_b64_tr_b16 v[78:79], v78 offset:9792
	ds_read_b128 v[84:87], v84
	v_add_u32_e32 v88, 0x1e900, v149
	s_waitcnt lgkmcnt(0)
	v_mfma_f32_16x16x32_bf16 v[84:87], v[84:87], v[80:83], v[90:93]
	s_nop 2
	ds_read_b128 v[88:91], v88
	v_add_u32_e32 v92, 0x1f200, v149
	s_waitcnt lgkmcnt(0)
	v_mfma_f32_16x16x32_bf16 v[88:91], v[88:91], v[80:83], v[94:97]
	s_nop 2
	ds_read_b128 v[92:95], v92
	v_add_u32_e32 v96, 0x1f240, v149
	ds_read_b128 v[96:99], v96
	s_waitcnt lgkmcnt(1)
	v_mfma_f32_16x16x32_bf16 v[92:95], v[92:95], v[80:83], v[102:105]
	s_nop 2
	v_add_u32_e32 v102, 0x1fb40, v149
	ds_read_b128 v[102:105], v102
	s_waitcnt lgkmcnt(1)
	v_mfma_f32_16x16x32_bf16 v[92:95], v[96:99], v[76:79], v[92:95]
	v_add_u32_e32 v96, 0x1fb00, v149
	ds_read_b128 v[96:99], v96
	s_waitcnt lgkmcnt(0)
	v_mfma_f32_16x16x32_bf16 v[96:99], v[96:99], v[80:83], v[106:109]
	v_mfma_f32_16x16x32_bf16 v[96:99], v[102:105], v[76:79], v[96:99]
	s_cbranch_vccnz .LBB0_820
	v_add_u32_e32 v101, 0, v101
	v_cvt_pk_bf16_f32 v84, v84, s0
	ds_write_b16 v101, v84
	v_cvt_pk_bf16_f32 v84, v85, s0
	ds_write_b16 v101, v84 offset:272
	v_cvt_pk_bf16_f32 v84, v86, s0
	ds_write_b16 v101, v84 offset:544
	v_cvt_pk_bf16_f32 v84, v87, s0
	ds_write_b16 v101, v84 offset:816
	v_cvt_pk_bf16_f32 v84, v88, s0
	ds_write_b16 v101, v84 offset:4352
	v_cvt_pk_bf16_f32 v84, v89, s0
	ds_write_b16 v101, v84 offset:4624
	v_cvt_pk_bf16_f32 v84, v90, s0
	ds_write_b16 v101, v84 offset:4896
	v_cvt_pk_bf16_f32 v84, v91, s0
	ds_write_b16 v101, v84 offset:5168
	v_cvt_pk_bf16_f32 v84, v92, s0
	ds_write_b16 v101, v84 offset:8704
	v_cvt_pk_bf16_f32 v84, v93, s0
	ds_write_b16 v101, v84 offset:8976
	v_cvt_pk_bf16_f32 v84, v94, s0
	ds_write_b16 v101, v84 offset:9248
	v_cvt_pk_bf16_f32 v84, v95, s0
	ds_write_b16 v101, v84 offset:9520
	v_cvt_pk_bf16_f32 v84, v96, s0
	ds_write_b16 v101, v84 offset:13056
	v_cvt_pk_bf16_f32 v84, v97, s0
	ds_write_b16 v101, v84 offset:13328
	v_cvt_pk_bf16_f32 v84, v98, s0
	ds_write_b16 v101, v84 offset:13600
	v_cvt_pk_bf16_f32 v84, v99, s0
	ds_write_b16 v101, v84 offset:13872
